# no store drain between the q/k/gate GEMM and the V^T GEMM (stores of the last epilogue overlap the next prologue loads)
# speedup vs baseline: 1.0022x; 1.0022x over previous
; #define PG8_WAIT_V(n) asm volatile("s_waitcnt vmcnt(" #n ")" ::: "memory")
; #define PG8_BAR __builtin_amdgcn_s_barrier()
; template <class Epi, class Sched, bool ALIGN_EPI = false, bool SP2 = false>
; __device__ __forceinline__ void gemm_phase(PG8_LAS unsigned char* lds, const Gemm g, const Sched& S, const Epi& E) {
;     ...
;     PG8_WAIT_V(0);
;     if constexpr (!ALIGN_EPI) { if (wr == 0) PG8_BAR; }
;     PG8_BAR;
.LBB0_560:
	s_nop 0
	s_barrier
